# kv epilogue: the four k-norm weight loads per 16-row block issued together with counted vmcnt(3) waits (no per-load drain of the previous K store); on top of scan lgkm ladder
# speedup vs baseline: 1.0136x; 1.0077x over previous
; DI u32x2 pack4(f32x4 v) { return u32x2{pack2(v[0], v[1]), pack2(v[2], v[3])}; }
; DI void kv_tile(const int tid_, const Params& p, int l, int mtile, int h, char* s0, char* s1, char* s2) {
;     ...
;       float ss = 0.f;
; #pragma unroll
;       for (int nt = 0; nt < 4; ++nt) {
;         acc[mt][nt] *= rs;
;         ss += acc[mt][nt][0] * acc[mt][nt][0] + acc[mt][nt][1] * acc[mt][nt][1] + acc[mt][nt][2] * acc[mt][nt][2] + acc[mt][nt][3] * acc[mt][nt][3];
;       }
;       ss = xor_sum(ss, 16); ss = xor_sum(ss, 32);
;       const float rn = rsqrtf(ss * (1.f / 64.f) + 1e-6f);
; #pragma unroll
;       for (int nt = 0; nt < 4; ++nt) {
;         const int n = nt * 16 + g * 4;
;         f32x4 gw = ld4(p.in[I_KNN] + l * 64 + n);
;         *(u32x2*)(KN + krow * 512 + h * 64 + n) = pack4(acc[mt][nt] * gw * rn);
;       }
.LBB0_370:
	v_lshrrev_b32_e32 v67, 2, v74
	v_pk_mul_f32 v[82:83], v[50:51], v[66:67] op_sel_hi:[1,0]
	v_pk_mul_f32 v[62:63], v[62:63], v[66:67] op_sel_hi:[1,0]
	v_mul_f32_e32 v50, v83, v83
	v_mul_f32_e32 v51, v63, v63
	v_pk_mul_f32 v[80:81], v[52:53], v[66:67] op_sel_hi:[1,0]
	v_fmac_f32_e32 v50, v82, v82
	v_pk_mul_f32 v[64:65], v[64:65], v[66:67] op_sel_hi:[1,0]
	v_fmac_f32_e32 v51, v62, v62
	v_fmac_f32_e32 v50, v80, v80
	v_fmac_f32_e32 v51, v64, v64
	v_fmac_f32_e32 v50, v81, v81
	v_fmac_f32_e32 v51, v65, v65
	v_pk_mul_f32 v[58:59], v[58:59], v[66:67] op_sel_hi:[1,0]
	v_add_f32_e32 v50, v50, v51
	v_mul_f32_e32 v51, v59, v59
	v_pk_mul_f32 v[60:61], v[60:61], v[66:67] op_sel_hi:[1,0]
	v_fmac_f32_e32 v51, v58, v58
	v_fmac_f32_e32 v51, v60, v60
	v_fmac_f32_e32 v51, v61, v61
	v_pk_mul_f32 v[54:55], v[54:55], v[66:67] op_sel_hi:[1,0]
	v_add_f32_e32 v50, v51, v50
	v_mul_f32_e32 v51, v55, v55
	v_pk_mul_f32 v[52:53], v[56:57], v[66:67] op_sel_hi:[1,0]
	v_fmac_f32_e32 v51, v54, v54
	v_fmac_f32_e32 v51, v52, v52
	v_fmac_f32_e32 v51, v53, v53
	v_add_f32_e32 v50, v51, v50
	v_mov_b32_e32 v51, v50
	s_nop 1
	v_permlane16_swap_b32_e32 v50, v51
	v_add_f32_e32 v50, v50, v51
	v_mov_b32_e32 v51, v50
	s_nop 1
	v_permlane32_swap_b32_e32 v50, v51
	v_add_f32_e32 v50, v50, v51
	v_fmamk_f32 v50, v50, 0x3c800000, v132
	v_cmp_gt_f32_e32 vcc, s22, v50
	v_mul_f32_e32 v51, 0x4b800000, v50
	v_and_b32_e32 v70, 12, v67
	v_cndmask_b32_e32 v50, v50, v51, vcc
	v_rsq_f32_e32 v50, v50
	v_lshlrev_b64 v[66:67], 10, v[68:69]
	s_add_u32 s8, s88, s21
	s_addc_u32 s9, s89, s56
	v_mul_f32_e32 v51, 0x45800000, v50
	v_cndmask_b32_e32 v56, v50, v51, vcc
	v_lshlrev_b32_e32 v50, 2, v70
	v_mov_b32_e32 v51, v1
	v_lshl_add_u64 v[50:51], s[86:87], 0, v[50:51]
	flat_load_dwordx4 v[76:79], v[50:51]
	flat_load_dwordx4 v[210:213], v[50:51] offset:64
	flat_load_dwordx4 v[214:217], v[50:51] offset:128
	flat_load_dwordx4 v[218:221], v[50:51] offset:192
	s_and_b64 vcc, exec, s[44:45]
	s_waitcnt vmcnt(3) lgkmcnt(0)
	v_pk_mul_f32 v[68:69], v[80:81], v[78:79]
	v_pk_mul_f32 v[76:77], v[82:83], v[76:77]
	v_pk_mul_f32 v[68:69], v[68:69], v[56:57] op_sel_hi:[1,0]
	v_pk_mul_f32 v[76:77], v[76:77], v[56:57] op_sel_hi:[1,0]
	s_nop 0
	v_cvt_pk_bf16_f32 v76, v76, v77
	v_cvt_pk_bf16_f32 v77, v68, v69
	v_and_b32_e32 v68, 24, v72
	v_or_b32_e32 v66, v66, v68
	v_lshl_add_u64 v[66:67], s[8:9], 0, v[66:67]
	flat_store_dwordx2 v[66:67], v[76:77]
	s_waitcnt vmcnt(3)
	v_pk_mul_f32 v[64:65], v[64:65], v[212:213]
	v_pk_mul_f32 v[62:63], v[62:63], v[210:211]
	v_pk_mul_f32 v[64:65], v[64:65], v[56:57] op_sel_hi:[1,0]
	v_pk_mul_f32 v[62:63], v[62:63], v[56:57] op_sel_hi:[1,0]
	s_nop 0
	v_cvt_pk_bf16_f32 v62, v62, v63
	v_cvt_pk_bf16_f32 v63, v64, v65
	flat_store_dwordx2 v[66:67], v[62:63] offset:32
	s_waitcnt vmcnt(3)
	v_pk_mul_f32 v[60:61], v[60:61], v[216:217]
	v_pk_mul_f32 v[58:59], v[58:59], v[214:215]
	v_pk_mul_f32 v[60:61], v[60:61], v[56:57] op_sel_hi:[1,0]
	v_pk_mul_f32 v[58:59], v[58:59], v[56:57] op_sel_hi:[1,0]
	s_nop 0
	v_cvt_pk_bf16_f32 v58, v58, v59
	v_cvt_pk_bf16_f32 v59, v60, v61
	flat_store_dwordx2 v[66:67], v[58:59] offset:64
	s_waitcnt vmcnt(3)
	v_pk_mul_f32 v[52:53], v[52:53], v[220:221]
	v_pk_mul_f32 v[54:55], v[54:55], v[218:219]
	v_pk_mul_f32 v[52:53], v[52:53], v[56:57] op_sel_hi:[1,0]
	v_pk_mul_f32 v[54:55], v[54:55], v[56:57] op_sel_hi:[1,0]
	v_mov_b32_e32 v58, 1.0
	v_cvt_pk_bf16_f32 v54, v54, v55
	v_cvt_pk_bf16_f32 v55, v52, v53
	v_or_b32_e32 v52, v73, v70
	flat_store_dwordx2 v[66:67], v[54:55] offset:96
	v_add_u32_e32 v56, s20, v52
	v_mov_b32_e32 v54, 1.0
	v_mov_b32_e32 v55, 1.0
	v_mov_b32_e32 v59, 1.0
	s_cbranch_vccz .LBB0_373
	s_and_b64 vcc, exec, s[42:43]
	s_mov_b64 s[8:9], -1
	s_cbranch_vccz .LBB0_374

; DI u32x2 pack4(f32x4 v) { return u32x2{pack2(v[0], v[1]), pack2(v[2], v[3])}; }
; DI void kv_tile(const int tid_, const Params& p, int l, int mtile, int h, char* s0, char* s1, char* s2) {
;     ...
;       float ss = 0.f;
; #pragma unroll
;       for (int nt = 0; nt < 4; ++nt) {
;         acc[mt][nt] *= rs;
;         ss += acc[mt][nt][0] * acc[mt][nt][0] + acc[mt][nt][1] * acc[mt][nt][1] + acc[mt][nt][2] * acc[mt][nt][2] + acc[mt][nt][3] * acc[mt][nt][3];
;       }
;       ss = xor_sum(ss, 16); ss = xor_sum(ss, 32);
;       const float rn = rsqrtf(ss * (1.f / 64.f) + 1e-6f);
; #pragma unroll
;       for (int nt = 0; nt < 4; ++nt) {
;         const int n = nt * 16 + g * 4;
;         f32x4 gw = ld4(p.in[I_KNN] + l * 64 + n);
;         *(u32x2*)(KN + krow * 512 + h * 64 + n) = pack4(acc[mt][nt] * gw * rn);
;       }
.LBB0_390:
	flat_load_dwordx4 v[54:57], v[50:51]
	flat_load_dwordx4 v[222:225], v[50:51] offset:64
	flat_load_dwordx4 v[226:229], v[50:51] offset:128
	flat_load_dwordx4 v[230:233], v[50:51] offset:192
	v_pk_mul_f32 v[48:49], v[18:19], v[36:37] op_sel_hi:[1,0]
	v_pk_mul_f32 v[30:31], v[30:31], v[36:37] op_sel_hi:[1,0]
	v_mul_f32_e32 v0, v49, v49
	v_mul_f32_e32 v18, v31, v31
	v_pk_mul_f32 v[44:45], v[20:21], v[36:37] op_sel_hi:[1,0]
	v_fmac_f32_e32 v0, v48, v48
	v_pk_mul_f32 v[32:33], v[32:33], v[36:37] op_sel_hi:[1,0]
	v_fmac_f32_e32 v18, v30, v30
	v_fmac_f32_e32 v0, v44, v44
	v_fmac_f32_e32 v18, v32, v32
	v_fmac_f32_e32 v0, v45, v45
	v_fmac_f32_e32 v18, v33, v33
	v_pk_mul_f32 v[26:27], v[26:27], v[36:37] op_sel_hi:[1,0]
	v_add_f32_e32 v0, v0, v18
	v_mul_f32_e32 v18, v27, v27
	v_pk_mul_f32 v[28:29], v[28:29], v[36:37] op_sel_hi:[1,0]
	v_fmac_f32_e32 v18, v26, v26
	v_fmac_f32_e32 v18, v28, v28
	v_pk_mul_f32 v[20:21], v[22:23], v[36:37] op_sel_hi:[1,0]
	v_fmac_f32_e32 v18, v29, v29
	v_mul_f32_e32 v22, v21, v21
	v_add_f32_e32 v0, v18, v0
	v_pk_mul_f32 v[18:19], v[24:25], v[36:37] op_sel_hi:[1,0]
	v_fmac_f32_e32 v22, v20, v20
	v_fmac_f32_e32 v22, v18, v18
	v_fmac_f32_e32 v22, v19, v19
	v_add_f32_e32 v0, v22, v0
	v_mov_b32_e32 v22, v0
	s_nop 1
	v_permlane16_swap_b32_e32 v0, v22
	v_add_f32_e32 v0, v0, v22
	v_mov_b32_e32 v22, v0
	s_nop 1
	v_permlane32_swap_b32_e32 v0, v22
	v_add_f32_e32 v0, v0, v22
	v_fmamk_f32 v0, v0, 0x3c800000, v132
	v_cmp_gt_f32_e32 vcc, s22, v0
	v_mul_f32_e32 v22, 0x4b800000, v0
	s_add_u32 s8, s88, s21
	v_cndmask_b32_e32 v0, v0, v22, vcc
	v_rsq_f32_e32 v0, v0
	s_addc_u32 s9, s89, s56
	v_mul_f32_e32 v22, 0x45800000, v0
	v_cndmask_b32_e32 v0, v0, v22, vcc
	v_lshlrev_b64 v[22:23], 10, v[40:41]
	v_or_b32_e32 v22, v22, v68
	v_lshl_add_u64 v[40:41], s[8:9], 0, v[22:23]
	s_and_b64 vcc, exec, s[44:45]
	s_waitcnt vmcnt(3) lgkmcnt(0)
	v_pk_mul_f32 v[24:25], v[44:45], v[56:57]
	v_pk_mul_f32 v[36:37], v[48:49], v[54:55]
	v_pk_mul_f32 v[24:25], v[24:25], v[0:1] op_sel_hi:[1,0]
	v_pk_mul_f32 v[36:37], v[36:37], v[0:1] op_sel_hi:[1,0]
	s_nop 0
	v_cvt_pk_bf16_f32 v36, v36, v37
	v_cvt_pk_bf16_f32 v37, v24, v25
	flat_store_dwordx2 v[40:41], v[36:37]
	s_waitcnt vmcnt(3)
	v_pk_mul_f32 v[24:25], v[32:33], v[224:225]
	v_pk_mul_f32 v[22:23], v[30:31], v[222:223]
	v_pk_mul_f32 v[24:25], v[24:25], v[0:1] op_sel_hi:[1,0]
	v_pk_mul_f32 v[22:23], v[22:23], v[0:1] op_sel_hi:[1,0]
	s_nop 0
	v_cvt_pk_bf16_f32 v22, v22, v23
	v_cvt_pk_bf16_f32 v23, v24, v25
	flat_store_dwordx2 v[40:41], v[22:23] offset:32
	s_waitcnt vmcnt(3)
	v_pk_mul_f32 v[24:25], v[28:29], v[228:229]
	v_pk_mul_f32 v[22:23], v[26:27], v[226:227]
	v_pk_mul_f32 v[24:25], v[24:25], v[0:1] op_sel_hi:[1,0]
	v_pk_mul_f32 v[22:23], v[22:23], v[0:1] op_sel_hi:[1,0]
	s_nop 0
	v_cvt_pk_bf16_f32 v22, v22, v23
	v_cvt_pk_bf16_f32 v23, v24, v25
	flat_store_dwordx2 v[40:41], v[22:23] offset:64
	s_waitcnt vmcnt(3)
	v_pk_mul_f32 v[18:19], v[18:19], v[232:233]
	v_pk_mul_f32 v[20:21], v[20:21], v[230:231]
	v_pk_mul_f32 v[18:19], v[18:19], v[0:1] op_sel_hi:[1,0]
	v_pk_mul_f32 v[20:21], v[20:21], v[0:1] op_sel_hi:[1,0]
	v_or_b32_e32 v0, v35, v70
	v_cvt_pk_bf16_f32 v20, v20, v21
	v_cvt_pk_bf16_f32 v21, v18, v19
	flat_store_dwordx2 v[40:41], v[20:21] offset:96
	v_add_u32_e32 v20, s20, v0
	v_mov_b32_e32 v18, 1.0
	v_mov_b32_e32 v19, 1.0
	v_mov_b32_e32 v22, 1.0
	v_mov_b32_e32 v23, 1.0
	s_cbranch_vccz .LBB0_393
	s_and_b64 vcc, exec, s[42:43]
	s_mov_b64 s[8:9], -1
	s_cbranch_vccz .LBB0_394
